# v82 + G2a gate epilogue: six of the ai=1 half's eight gate loads issued together with the ai=0 half's (renamed into unused registers) instead of behind the ai=0 T stores
# speedup vs baseline: 1.0071x; 1.0054x over previous
; __device__ __forceinline__ unsigned cvt_pk_bf16(float lo, float hi) { const f32x2_t v = {lo, hi}; const bf16x2_t c = __builtin_convertvector(v, bf16x2_t); return __builtin_bit_cast(unsigned, c); }
; __device__ __forceinline__ float bf_lo(unsigned w) { return __uint_as_float(w << 16); }
; __device__ __forceinline__ float bf_hi(unsigned w) { return __uint_as_float(w & 0xffff0000u); }
; __device__ __forceinline__ float sigmoidf_fast(float x) { return __builtin_amdgcn_rcpf(1.0f + __expf(-x)); }
;     __device__ __forceinline__ void operator()(const f32x4 (&acc)[2][2][4][2], const Unit& u, int wr, int wc, int fr, int fq) const {
;     ...
;         for (int ai = 0; ai < 2; ++ai) { u32x4 gq[4][2];
; #pragma unroll
;             for (int m = 0; m < 4; ++m)
; #pragma unroll
;                 for (int bj = 0; bj < 2; ++bj) gq[m][bj] = *(const u32x4*)(G + (size_t)(row0 + ai * HALF + m * 16) * ldg + col0 + bj * HALF);
; #pragma unroll
;             for (int m = 0; m < 4; ++m) { const size_t r = (size_t)(row0 + ai * HALF + m * 16);
; #pragma unroll
;                 for (int bj = 0; bj < 2; ++bj) { const u32x4 gw = gq[m][bj]; const f32x4 a0 = acc[ai][bj][m][0], a1 = acc[ai][bj][m][1];
;                     u32x4 w; w.x = cvt_pk_bf16(sigmoidf_fast(bf_lo(gw.x)) * a0[0], sigmoidf_fast(bf_hi(gw.x)) * a0[1]); w.y = cvt_pk_bf16(sigmoidf_fast(bf_lo(gw.y)) * a0[2], sigmoidf_fast(bf_hi(gw.y)) * a0[3]);
;                     w.z = cvt_pk_bf16(sigmoidf_fast(bf_lo(gw.z)) * a1[0], sigmoidf_fast(bf_hi(gw.z)) * a1[1]); w.w = cvt_pk_bf16(sigmoidf_fast(bf_lo(gw.w)) * a1[2], sigmoidf_fast(bf_hi(gw.w)) * a1[3]);
;                     *(u32x4*)(T + r * ldt + col0 + bj * HALF) = w; } }
.LBB0_849:
	v_lshl_or_b32 v34, s25, 8, v189
	v_ashrrev_i32_e32 v35, 31, v34
	v_readlane_b32 s16, v253, 18
	v_lshlrev_b64 v[34:35], 1, v[34:35]
	v_readlane_b32 s17, v253, 19
	v_lshl_add_u32 v174, s24, 8, v186
	v_or_b32_e32 v182, 16, v174
	v_lshl_add_u64 v[176:177], s[16:17], 0, v[34:35]
	v_mad_i64_i32 v[100:101], s[16:17], v174, s67, v[176:177]
	global_load_dwordx4 v[198:201], v[100:101], off
	global_load_dwordx4 v[152:155], v[100:101], off offset:256
	v_mad_i64_i32 v[100:101], s[16:17], v182, s67, v[176:177]
	global_load_dwordx4 v[144:147], v[100:101], off
	global_load_dwordx4 v[140:143], v[100:101], off offset:256
	v_or_b32_e32 v180, 32, v174
	v_mad_i64_i32 v[100:101], s[16:17], v180, s67, v[176:177]
	global_load_dwordx4 v[136:139], v[100:101], off
	global_load_dwordx4 v[124:127], v[100:101], off offset:256
	v_or_b32_e32 v178, 48, v174
	v_mad_i64_i32 v[100:101], s[16:17], v178, s67, v[176:177]
	global_load_dwordx4 v[112:115], v[100:101], off
	s_nop 0
	global_load_dwordx4 v[100:103], v[100:101], off offset:256
	v_ashrrev_i32_e32 v175, 31, v174
	v_ashrrev_i32_e32 v183, 31, v182
	v_ashrrev_i32_e32 v181, 31, v180
	v_ashrrev_i32_e32 v179, 31, v178
	v_readlane_b32 s22, v252, 55
	v_readlane_b32 s23, v252, 56
	s_andn2_b64 vcc, exec, s[12:13]
	v_add_u32_e32 v226, 0x80, v174
	v_mad_i64_i32 v[248:249], s[16:17], v226, s67, v[176:177]
	global_load_dwordx4 v[202:205], v[248:249], off
	global_load_dwordx4 v[206:209], v[248:249], off offset:256
	v_add_u32_e32 v226, 0x90, v174
	v_mad_i64_i32 v[248:249], s[16:17], v226, s67, v[176:177]
	global_load_dwordx4 v[210:213], v[248:249], off
	global_load_dwordx4 v[214:217], v[248:249], off offset:256
	v_add_u32_e32 v226, 0xa0, v174
	v_mad_i64_i32 v[248:249], s[16:17], v226, s67, v[176:177]
	global_load_dwordx4 v[218:221], v[248:249], off
	global_load_dwordx4 v[222:225], v[248:249], off offset:256
	s_waitcnt vmcnt(6)
	v_lshlrev_b32_e32 v32, 16, v198
	v_mul_f32_e32 v32, 0xbfb8aa3b, v32
	v_exp_f32_e32 v32, v32
	s_nop 0
	v_add_f32_e32 v32, 1.0, v32
	v_rcp_f32_e32 v192, v32
	v_and_b32_e32 v32, 0xffff0000, v198
	v_mul_f32_e32 v32, 0xbfb8aa3b, v32
	v_exp_f32_e32 v32, v32
	s_nop 0
	v_add_f32_e32 v32, 1.0, v32
	v_rcp_f32_e32 v193, v32
	v_lshlrev_b32_e32 v32, 16, v199
	v_mul_f32_e32 v32, 0xbfb8aa3b, v32
	v_exp_f32_e32 v32, v32
	v_pk_mul_f32 v[156:157], v[156:157], v[192:193]
	v_add_f32_e32 v32, 1.0, v32
	v_rcp_f32_e32 v192, v32
	v_and_b32_e32 v32, 0xffff0000, v199
	v_mul_f32_e32 v32, 0xbfb8aa3b, v32
	v_exp_f32_e32 v32, v32
	v_cvt_pk_bf16_f32 v156, v156, v157
	v_add_f32_e32 v32, 1.0, v32
	v_rcp_f32_e32 v193, v32
	v_lshlrev_b32_e32 v32, 16, v200
	v_mul_f32_e32 v32, 0xbfb8aa3b, v32
	v_exp_f32_e32 v32, v32
	v_pk_mul_f32 v[158:159], v[158:159], v[192:193]
	v_add_f32_e32 v32, 1.0, v32
	v_cvt_pk_bf16_f32 v157, v158, v159
	v_rcp_f32_e32 v158, v32
	v_and_b32_e32 v32, 0xffff0000, v200
	v_mul_f32_e32 v32, 0xbfb8aa3b, v32
	v_exp_f32_e32 v32, v32
	s_nop 0
	v_add_f32_e32 v32, 1.0, v32
	v_rcp_f32_e32 v159, v32
	v_lshlrev_b32_e32 v32, 16, v201
	v_mul_f32_e32 v32, 0xbfb8aa3b, v32
	v_exp_f32_e32 v32, v32
	v_pk_mul_f32 v[148:149], v[148:149], v[158:159]
	v_add_f32_e32 v32, 1.0, v32
	v_cvt_pk_bf16_f32 v158, v148, v149
	v_rcp_f32_e32 v148, v32
	v_and_b32_e32 v32, 0xffff0000, v201
	v_mul_f32_e32 v32, 0xbfb8aa3b, v32
	v_exp_f32_e32 v32, v32
	s_nop 0
	v_add_f32_e32 v32, 1.0, v32
	v_rcp_f32_e32 v149, v32
	v_lshlrev_b32_e32 v32, 16, v152
	v_mul_f32_e32 v32, 0xbfb8aa3b, v32
	v_exp_f32_e32 v32, v32
	v_pk_mul_f32 v[148:149], v[150:151], v[148:149]
	v_add_f32_e32 v32, 1.0, v32
	v_rcp_f32_e32 v150, v32
	v_and_b32_e32 v32, 0xffff0000, v152
	v_mul_f32_e32 v32, 0xbfb8aa3b, v32
	v_exp_f32_e32 v32, v32
	v_cvt_pk_bf16_f32 v159, v148, v149
	v_lshlrev_b64 v[148:149], 12, v[174:175]
	v_lshl_add_u64 v[148:149], s[22:23], 0, v[148:149]
	v_add_f32_e32 v32, 1.0, v32
	v_rcp_f32_e32 v151, v32
	v_lshlrev_b32_e32 v32, 16, v153
	v_mul_f32_e32 v32, 0xbfb8aa3b, v32
	v_exp_f32_e32 v32, v32
	v_pk_mul_f32 v[132:133], v[132:133], v[150:151]
	v_lshl_add_u64 v[148:149], v[148:149], 0, v[34:35]
	v_cvt_pk_bf16_f32 v132, v132, v133
	v_add_f32_e32 v32, 1.0, v32
	v_rcp_f32_e32 v150, v32
	v_and_b32_e32 v32, 0xffff0000, v153
	v_mul_f32_e32 v32, 0xbfb8aa3b, v32
	v_exp_f32_e32 v32, v32
	global_store_dwordx4 v[148:149], v[156:159], off
	v_add_f32_e32 v32, 1.0, v32
	v_rcp_f32_e32 v151, v32
	v_lshlrev_b32_e32 v32, 16, v154
	v_mul_f32_e32 v32, 0xbfb8aa3b, v32
	v_exp_f32_e32 v32, v32
	v_pk_mul_f32 v[134:135], v[134:135], v[150:151]
	v_add_f32_e32 v32, 1.0, v32
	v_cvt_pk_bf16_f32 v133, v134, v135
	v_rcp_f32_e32 v134, v32
	v_and_b32_e32 v32, 0xffff0000, v154
	v_mul_f32_e32 v32, 0xbfb8aa3b, v32
	v_exp_f32_e32 v32, v32
	s_nop 0
	v_add_f32_e32 v32, 1.0, v32
	v_rcp_f32_e32 v135, v32
	v_lshlrev_b32_e32 v32, 16, v155
	v_mul_f32_e32 v32, 0xbfb8aa3b, v32
	v_exp_f32_e32 v32, v32
	v_pk_mul_f32 v[128:129], v[128:129], v[134:135]
	v_add_f32_e32 v32, 1.0, v32
	v_cvt_pk_bf16_f32 v134, v128, v129
	v_rcp_f32_e32 v128, v32
	v_and_b32_e32 v32, 0xffff0000, v155
	v_mul_f32_e32 v32, 0xbfb8aa3b, v32
	v_exp_f32_e32 v32, v32
	s_nop 0
	v_add_f32_e32 v32, 1.0, v32
	v_rcp_f32_e32 v129, v32
	v_lshlrev_b32_e32 v32, 16, v144
	v_mul_f32_e32 v32, 0xbfb8aa3b, v32
	v_exp_f32_e32 v32, v32
	v_pk_mul_f32 v[128:129], v[130:131], v[128:129]
	v_add_f32_e32 v32, 1.0, v32
	v_cvt_pk_bf16_f32 v135, v128, v129
	v_rcp_f32_e32 v128, v32
	v_and_b32_e32 v32, 0xffff0000, v144
	v_mul_f32_e32 v32, 0xbfb8aa3b, v32
	v_exp_f32_e32 v32, v32
	global_store_dwordx4 v[148:149], v[132:135], off offset:256
	v_add_f32_e32 v32, 1.0, v32
	v_rcp_f32_e32 v129, v32
	v_lshlrev_b32_e32 v32, 16, v145
	v_mul_f32_e32 v32, 0xbfb8aa3b, v32
	v_exp_f32_e32 v32, v32
; __device__ __forceinline__ unsigned cvt_pk_bf16(float lo, float hi) { const f32x2_t v = {lo, hi}; const bf16x2_t c = __builtin_convertvector(v, bf16x2_t); return __builtin_bit_cast(unsigned, c); }
; __device__ __forceinline__ float bf_lo(unsigned w) { return __uint_as_float(w << 16); }
; __device__ __forceinline__ float bf_hi(unsigned w) { return __uint_as_float(w & 0xffff0000u); }
; __device__ __forceinline__ float sigmoidf_fast(float x) { return __builtin_amdgcn_rcpf(1.0f + __expf(-x)); }
;     __device__ __forceinline__ void operator()(const f32x4 (&acc)[2][2][4][2], const Unit& u, int wr, int wc, int fr, int fq) const {
;     ...
;             for (int m = 0; m < 4; ++m) { const size_t r = (size_t)(row0 + ai * HALF + m * 16);
; #pragma unroll
;                 for (int bj = 0; bj < 2; ++bj) { const u32x4 gw = gq[m][bj]; const f32x4 a0 = acc[ai][bj][m][0], a1 = acc[ai][bj][m][1];
;                     u32x4 w; w.x = cvt_pk_bf16(sigmoidf_fast(bf_lo(gw.x)) * a0[0], sigmoidf_fast(bf_hi(gw.x)) * a0[1]); w.y = cvt_pk_bf16(sigmoidf_fast(bf_lo(gw.y)) * a0[2], sigmoidf_fast(bf_hi(gw.y)) * a0[3]);
;                     w.z = cvt_pk_bf16(sigmoidf_fast(bf_lo(gw.z)) * a1[0], sigmoidf_fast(bf_hi(gw.z)) * a1[1]); w.w = cvt_pk_bf16(sigmoidf_fast(bf_lo(gw.w)) * a1[2], sigmoidf_fast(bf_hi(gw.w)) * a1[3]);
;                     *(u32x4*)(T + r * ldt + col0 + bj * HALF) = w; } }
	v_pk_mul_f32 v[120:121], v[120:121], v[128:129]
	v_add_f32_e32 v32, 1.0, v32
	v_rcp_f32_e32 v128, v32
	v_and_b32_e32 v32, 0xffff0000, v145
	v_mul_f32_e32 v32, 0xbfb8aa3b, v32
	v_exp_f32_e32 v32, v32
	v_cvt_pk_bf16_f32 v120, v120, v121
	v_add_f32_e32 v32, 1.0, v32
	v_rcp_f32_e32 v129, v32
	v_lshlrev_b32_e32 v32, 16, v146
	v_mul_f32_e32 v32, 0xbfb8aa3b, v32
	v_exp_f32_e32 v32, v32
	v_pk_mul_f32 v[122:123], v[122:123], v[128:129]
	v_add_f32_e32 v32, 1.0, v32
	v_cvt_pk_bf16_f32 v121, v122, v123
	v_rcp_f32_e32 v122, v32
	v_and_b32_e32 v32, 0xffff0000, v146
	v_mul_f32_e32 v32, 0xbfb8aa3b, v32
	v_exp_f32_e32 v32, v32
	s_nop 0
	v_add_f32_e32 v32, 1.0, v32
	v_rcp_f32_e32 v123, v32
	v_lshlrev_b32_e32 v32, 16, v147
	v_mul_f32_e32 v32, 0xbfb8aa3b, v32
	v_exp_f32_e32 v32, v32
	v_pk_mul_f32 v[116:117], v[116:117], v[122:123]
	v_add_f32_e32 v32, 1.0, v32
	v_cvt_pk_bf16_f32 v122, v116, v117
	v_rcp_f32_e32 v116, v32
	v_and_b32_e32 v32, 0xffff0000, v147
	v_mul_f32_e32 v32, 0xbfb8aa3b, v32
	v_exp_f32_e32 v32, v32
	s_nop 0
	v_add_f32_e32 v32, 1.0, v32
	v_rcp_f32_e32 v117, v32
	v_lshlrev_b32_e32 v32, 16, v140
	v_mul_f32_e32 v32, 0xbfb8aa3b, v32
	v_exp_f32_e32 v32, v32
	v_pk_mul_f32 v[116:117], v[118:119], v[116:117]
	v_add_f32_e32 v32, 1.0, v32
	v_rcp_f32_e32 v118, v32
	v_and_b32_e32 v32, 0xffff0000, v140
	v_mul_f32_e32 v32, 0xbfb8aa3b, v32
	v_exp_f32_e32 v32, v32
	v_cvt_pk_bf16_f32 v123, v116, v117
	v_lshlrev_b64 v[116:117], 12, v[182:183]
	v_lshl_add_u64 v[116:117], s[22:23], 0, v[116:117]
	v_add_f32_e32 v32, 1.0, v32
	v_rcp_f32_e32 v119, v32
	v_lshlrev_b32_e32 v32, 16, v141
	v_mul_f32_e32 v32, 0xbfb8aa3b, v32
	v_exp_f32_e32 v32, v32
	v_pk_mul_f32 v[108:109], v[108:109], v[118:119]
	v_lshl_add_u64 v[116:117], v[116:117], 0, v[34:35]
	v_cvt_pk_bf16_f32 v108, v108, v109
	v_add_f32_e32 v32, 1.0, v32
	v_rcp_f32_e32 v118, v32
	v_and_b32_e32 v32, 0xffff0000, v141
	v_mul_f32_e32 v32, 0xbfb8aa3b, v32
	v_exp_f32_e32 v32, v32
	global_store_dwordx4 v[116:117], v[120:123], off
	v_add_f32_e32 v32, 1.0, v32
	v_rcp_f32_e32 v119, v32
	v_lshlrev_b32_e32 v32, 16, v142
	v_mul_f32_e32 v32, 0xbfb8aa3b, v32
	v_exp_f32_e32 v32, v32
	v_pk_mul_f32 v[110:111], v[110:111], v[118:119]
	v_add_f32_e32 v32, 1.0, v32
	v_cvt_pk_bf16_f32 v109, v110, v111
	v_rcp_f32_e32 v110, v32
	v_and_b32_e32 v32, 0xffff0000, v142
	v_mul_f32_e32 v32, 0xbfb8aa3b, v32
	v_exp_f32_e32 v32, v32
	s_nop 0
	v_add_f32_e32 v32, 1.0, v32
	v_rcp_f32_e32 v111, v32
	v_lshlrev_b32_e32 v32, 16, v143
	v_mul_f32_e32 v32, 0xbfb8aa3b, v32
	v_exp_f32_e32 v32, v32
	v_pk_mul_f32 v[104:105], v[104:105], v[110:111]
	v_add_f32_e32 v32, 1.0, v32
	v_cvt_pk_bf16_f32 v110, v104, v105
	v_rcp_f32_e32 v104, v32
	v_and_b32_e32 v32, 0xffff0000, v143
	v_mul_f32_e32 v32, 0xbfb8aa3b, v32
	v_exp_f32_e32 v32, v32
	s_nop 0
	v_add_f32_e32 v32, 1.0, v32
	v_rcp_f32_e32 v105, v32
	v_lshlrev_b32_e32 v32, 16, v136
	v_mul_f32_e32 v32, 0xbfb8aa3b, v32
	v_exp_f32_e32 v32, v32
	v_pk_mul_f32 v[104:105], v[106:107], v[104:105]
	v_add_u32_e32 v106, 0x80, v174
	v_cvt_pk_bf16_f32 v111, v104, v105
	v_add_f32_e32 v32, 1.0, v32
	v_rcp_f32_e32 v104, v32
	v_and_b32_e32 v32, 0xffff0000, v136
	v_mul_f32_e32 v32, 0xbfb8aa3b, v32
	v_exp_f32_e32 v32, v32
	global_store_dwordx4 v[116:117], v[108:111], off offset:256
	v_ashrrev_i32_e32 v107, 31, v106
	v_add_f32_e32 v32, 1.0, v32
	v_rcp_f32_e32 v105, v32
	v_lshlrev_b32_e32 v32, 16, v137
	v_mul_f32_e32 v32, 0xbfb8aa3b, v32
	v_exp_f32_e32 v32, v32
	v_pk_mul_f32 v[96:97], v[96:97], v[104:105]
	v_add_f32_e32 v32, 1.0, v32
	v_rcp_f32_e32 v104, v32
	v_and_b32_e32 v32, 0xffff0000, v137
	v_mul_f32_e32 v32, 0xbfb8aa3b, v32
	v_exp_f32_e32 v32, v32
	v_cvt_pk_bf16_f32 v96, v96, v97
	v_add_f32_e32 v32, 1.0, v32
	v_rcp_f32_e32 v105, v32
	v_lshlrev_b32_e32 v32, 16, v138
	v_mul_f32_e32 v32, 0xbfb8aa3b, v32
	v_exp_f32_e32 v32, v32
	v_pk_mul_f32 v[98:99], v[98:99], v[104:105]
	v_add_f32_e32 v32, 1.0, v32
	v_cvt_pk_bf16_f32 v97, v98, v99
	v_rcp_f32_e32 v98, v32
	v_and_b32_e32 v32, 0xffff0000, v138
	v_mul_f32_e32 v32, 0xbfb8aa3b, v32
	v_exp_f32_e32 v32, v32
	s_nop 0
	v_add_f32_e32 v32, 1.0, v32
	v_rcp_f32_e32 v99, v32
	v_lshlrev_b32_e32 v32, 16, v139
	v_mul_f32_e32 v32, 0xbfb8aa3b, v32
	v_exp_f32_e32 v32, v32
	v_pk_mul_f32 v[92:93], v[92:93], v[98:99]
	v_add_f32_e32 v32, 1.0, v32
	v_cvt_pk_bf16_f32 v98, v92, v93
	v_rcp_f32_e32 v92, v32
	v_and_b32_e32 v32, 0xffff0000, v139
	v_mul_f32_e32 v32, 0xbfb8aa3b, v32
	v_exp_f32_e32 v32, v32
	s_nop 0
	v_add_f32_e32 v32, 1.0, v32
	v_rcp_f32_e32 v93, v32
	v_lshlrev_b32_e32 v32, 16, v124
	v_mul_f32_e32 v32, 0xbfb8aa3b, v32
	v_exp_f32_e32 v32, v32
	v_pk_mul_f32 v[92:93], v[94:95], v[92:93]
	v_add_f32_e32 v32, 1.0, v32
	v_rcp_f32_e32 v94, v32
	v_and_b32_e32 v32, 0xffff0000, v124
	v_mul_f32_e32 v32, 0xbfb8aa3b, v32
	v_exp_f32_e32 v32, v32
	v_cvt_pk_bf16_f32 v99, v92, v93
	v_lshlrev_b64 v[92:93], 12, v[180:181]
	v_lshl_add_u64 v[92:93], s[22:23], 0, v[92:93]
	v_add_f32_e32 v32, 1.0, v32
	v_rcp_f32_e32 v95, v32
	v_lshlrev_b32_e32 v32, 16, v125
	v_mul_f32_e32 v32, 0xbfb8aa3b, v32
	v_exp_f32_e32 v32, v32
	v_pk_mul_f32 v[88:89], v[88:89], v[94:95]
	v_lshl_add_u64 v[92:93], v[92:93], 0, v[34:35]
	v_cvt_pk_bf16_f32 v88, v88, v89
	v_add_f32_e32 v32, 1.0, v32
	v_rcp_f32_e32 v94, v32
	v_and_b32_e32 v32, 0xffff0000, v125
	v_mul_f32_e32 v32, 0xbfb8aa3b, v32
	v_exp_f32_e32 v32, v32
	global_store_dwordx4 v[92:93], v[96:99], off
	v_add_f32_e32 v32, 1.0, v32
	v_rcp_f32_e32 v95, v32
	v_lshlrev_b32_e32 v32, 16, v126
	v_mul_f32_e32 v32, 0xbfb8aa3b, v32
	v_exp_f32_e32 v32, v32
	v_pk_mul_f32 v[90:91], v[90:91], v[94:95]
	v_add_u32_e32 v98, 0xa0, v174
	v_cvt_pk_bf16_f32 v89, v90, v91
	v_add_f32_e32 v32, 1.0, v32
	v_rcp_f32_e32 v90, v32
; __device__ __forceinline__ unsigned cvt_pk_bf16(float lo, float hi) { const f32x2_t v = {lo, hi}; const bf16x2_t c = __builtin_convertvector(v, bf16x2_t); return __builtin_bit_cast(unsigned, c); }
; __device__ __forceinline__ float bf_lo(unsigned w) { return __uint_as_float(w << 16); }
; __device__ __forceinline__ float bf_hi(unsigned w) { return __uint_as_float(w & 0xffff0000u); }
; __device__ __forceinline__ float sigmoidf_fast(float x) { return __builtin_amdgcn_rcpf(1.0f + __expf(-x)); }
;     __device__ __forceinline__ void operator()(const f32x4 (&acc)[2][2][4][2], const Unit& u, int wr, int wc, int fr, int fq) const {
;     ...
;         for (int ai = 0; ai < 2; ++ai) { u32x4 gq[4][2];
; #pragma unroll
;             for (int m = 0; m < 4; ++m)
; #pragma unroll
;                 for (int bj = 0; bj < 2; ++bj) gq[m][bj] = *(const u32x4*)(G + (size_t)(row0 + ai * HALF + m * 16) * ldg + col0 + bj * HALF);
; #pragma unroll
;             for (int m = 0; m < 4; ++m) { const size_t r = (size_t)(row0 + ai * HALF + m * 16);
; #pragma unroll
;                 for (int bj = 0; bj < 2; ++bj) { const u32x4 gw = gq[m][bj]; const f32x4 a0 = acc[ai][bj][m][0], a1 = acc[ai][bj][m][1];
;                     u32x4 w; w.x = cvt_pk_bf16(sigmoidf_fast(bf_lo(gw.x)) * a0[0], sigmoidf_fast(bf_hi(gw.x)) * a0[1]); w.y = cvt_pk_bf16(sigmoidf_fast(bf_lo(gw.y)) * a0[2], sigmoidf_fast(bf_hi(gw.y)) * a0[3]);
;                     w.z = cvt_pk_bf16(sigmoidf_fast(bf_lo(gw.z)) * a1[0], sigmoidf_fast(bf_hi(gw.z)) * a1[1]); w.w = cvt_pk_bf16(sigmoidf_fast(bf_lo(gw.w)) * a1[2], sigmoidf_fast(bf_hi(gw.w)) * a1[3]);
;                     *(u32x4*)(T + r * ldt + col0 + bj * HALF) = w; } }
	v_and_b32_e32 v32, 0xffff0000, v126
	v_mul_f32_e32 v32, 0xbfb8aa3b, v32
	v_exp_f32_e32 v32, v32
	v_add_u32_e32 v96, 0xb0, v174
	v_ashrrev_i32_e32 v99, 31, v98
	v_ashrrev_i32_e32 v97, 31, v96
	v_add_f32_e32 v32, 1.0, v32
	v_rcp_f32_e32 v91, v32
	v_lshlrev_b32_e32 v32, 16, v127
	v_mul_f32_e32 v32, 0xbfb8aa3b, v32
	v_exp_f32_e32 v32, v32
	v_pk_mul_f32 v[84:85], v[84:85], v[90:91]
	v_add_f32_e32 v32, 1.0, v32
	v_cvt_pk_bf16_f32 v90, v84, v85
	v_rcp_f32_e32 v84, v32
	v_and_b32_e32 v32, 0xffff0000, v127
	v_mul_f32_e32 v32, 0xbfb8aa3b, v32
	v_exp_f32_e32 v32, v32
	s_nop 0
	v_add_f32_e32 v32, 1.0, v32
	v_rcp_f32_e32 v85, v32
	v_lshlrev_b32_e32 v32, 16, v112
	v_mul_f32_e32 v32, 0xbfb8aa3b, v32
	v_exp_f32_e32 v32, v32
	v_pk_mul_f32 v[84:85], v[86:87], v[84:85]
	v_add_f32_e32 v32, 1.0, v32
	v_cvt_pk_bf16_f32 v91, v84, v85
	v_rcp_f32_e32 v84, v32
	v_and_b32_e32 v32, 0xffff0000, v112
	v_mul_f32_e32 v32, 0xbfb8aa3b, v32
	v_exp_f32_e32 v32, v32
	global_store_dwordx4 v[92:93], v[88:91], off offset:256
	v_add_f32_e32 v32, 1.0, v32
	v_rcp_f32_e32 v85, v32
	v_lshlrev_b32_e32 v32, 16, v113
	v_mul_f32_e32 v32, 0xbfb8aa3b, v32
	v_exp_f32_e32 v32, v32
	v_pk_mul_f32 v[80:81], v[80:81], v[84:85]
	v_add_f32_e32 v32, 1.0, v32
	v_rcp_f32_e32 v84, v32
	v_and_b32_e32 v32, 0xffff0000, v113
	v_mul_f32_e32 v32, 0xbfb8aa3b, v32
	v_exp_f32_e32 v32, v32
	v_cvt_pk_bf16_f32 v80, v80, v81
	v_add_f32_e32 v32, 1.0, v32
	v_rcp_f32_e32 v85, v32
	v_lshlrev_b32_e32 v32, 16, v114
	v_mul_f32_e32 v32, 0xbfb8aa3b, v32
	v_exp_f32_e32 v32, v32
	v_pk_mul_f32 v[82:83], v[82:83], v[84:85]
	v_add_f32_e32 v32, 1.0, v32
	v_cvt_pk_bf16_f32 v81, v82, v83
	v_rcp_f32_e32 v82, v32
	v_and_b32_e32 v32, 0xffff0000, v114
	v_mul_f32_e32 v32, 0xbfb8aa3b, v32
	v_exp_f32_e32 v32, v32
	s_nop 0
	v_add_f32_e32 v32, 1.0, v32
	v_rcp_f32_e32 v83, v32
	v_lshlrev_b32_e32 v32, 16, v115
	v_mul_f32_e32 v32, 0xbfb8aa3b, v32
	v_exp_f32_e32 v32, v32
	v_pk_mul_f32 v[76:77], v[76:77], v[82:83]
	v_add_f32_e32 v32, 1.0, v32
	v_cvt_pk_bf16_f32 v82, v76, v77
	v_rcp_f32_e32 v76, v32
	v_and_b32_e32 v32, 0xffff0000, v115
	v_mul_f32_e32 v32, 0xbfb8aa3b, v32
	v_exp_f32_e32 v32, v32
	s_nop 0
	v_add_f32_e32 v32, 1.0, v32
	v_rcp_f32_e32 v77, v32
	v_lshlrev_b32_e32 v32, 16, v100
	v_mul_f32_e32 v32, 0xbfb8aa3b, v32
	v_exp_f32_e32 v32, v32
	v_pk_mul_f32 v[76:77], v[78:79], v[76:77]
	v_add_f32_e32 v32, 1.0, v32
	v_rcp_f32_e32 v78, v32
	v_and_b32_e32 v32, 0xffff0000, v100
	v_mul_f32_e32 v32, 0xbfb8aa3b, v32
	v_exp_f32_e32 v32, v32
	v_cvt_pk_bf16_f32 v83, v76, v77
	v_lshlrev_b64 v[76:77], 12, v[178:179]
	v_lshl_add_u64 v[76:77], s[22:23], 0, v[76:77]
	v_add_f32_e32 v32, 1.0, v32
	v_rcp_f32_e32 v79, v32
	v_lshlrev_b32_e32 v32, 16, v101
	v_mul_f32_e32 v32, 0xbfb8aa3b, v32
	v_exp_f32_e32 v32, v32
	v_pk_mul_f32 v[72:73], v[72:73], v[78:79]
	v_lshl_add_u64 v[76:77], v[76:77], 0, v[34:35]
	v_cvt_pk_bf16_f32 v72, v72, v73
	v_add_f32_e32 v32, 1.0, v32
	v_rcp_f32_e32 v78, v32
	v_and_b32_e32 v32, 0xffff0000, v101
	v_mul_f32_e32 v32, 0xbfb8aa3b, v32
	v_exp_f32_e32 v32, v32
	global_store_dwordx4 v[76:77], v[80:83], off
	v_add_u32_e32 v100, 0x90, v174
	v_ashrrev_i32_e32 v101, 31, v100
	v_add_f32_e32 v32, 1.0, v32
	v_rcp_f32_e32 v79, v32
	v_lshlrev_b32_e32 v32, 16, v102
	v_mul_f32_e32 v32, 0xbfb8aa3b, v32
	v_exp_f32_e32 v32, v32
	v_pk_mul_f32 v[74:75], v[74:75], v[78:79]
	v_add_f32_e32 v32, 1.0, v32
	v_cvt_pk_bf16_f32 v73, v74, v75
	v_rcp_f32_e32 v74, v32
	v_and_b32_e32 v32, 0xffff0000, v102
	v_mul_f32_e32 v32, 0xbfb8aa3b, v32
	v_exp_f32_e32 v32, v32
	s_nop 0
	v_add_f32_e32 v32, 1.0, v32
	v_rcp_f32_e32 v75, v32
	v_lshlrev_b32_e32 v32, 16, v103
	v_mul_f32_e32 v32, 0xbfb8aa3b, v32
	v_exp_f32_e32 v32, v32
	v_pk_mul_f32 v[68:69], v[68:69], v[74:75]
	v_add_f32_e32 v32, 1.0, v32
	v_cvt_pk_bf16_f32 v74, v68, v69
	v_rcp_f32_e32 v68, v32
	v_and_b32_e32 v32, 0xffff0000, v103
	v_mul_f32_e32 v32, 0xbfb8aa3b, v32
	v_exp_f32_e32 v32, v32
	s_nop 0
	v_add_f32_e32 v32, 1.0, v32
	v_rcp_f32_e32 v69, v32
	s_nop 0
	v_pk_mul_f32 v[68:69], v[70:71], v[68:69]
	s_nop 0
	v_cvt_pk_bf16_f32 v75, v68, v69
	global_store_dwordx4 v[76:77], v[72:75], off offset:256
	v_mad_i64_i32 v[68:69], s[16:17], v96, s67, v[176:177]
	global_load_dwordx4 v[72:75], v[68:69], off
	s_nop 0
	global_load_dwordx4 v[68:71], v[68:69], off offset:256
	s_mov_b64 s[16:17], -1
	s_waitcnt vmcnt(15)
	v_lshlrev_b32_e32 v32, 16, v202
	v_mul_f32_e32 v32, 0xbfb8aa3b, v32
	v_exp_f32_e32 v32, v32
	s_nop 0
	v_add_f32_e32 v32, 1.0, v32
	v_rcp_f32_e32 v108, v32
	v_and_b32_e32 v32, 0xffff0000, v202
	v_mul_f32_e32 v32, 0xbfb8aa3b, v32
	v_exp_f32_e32 v32, v32
	s_nop 0
	v_add_f32_e32 v32, 1.0, v32
	v_rcp_f32_e32 v109, v32
	v_lshlrev_b32_e32 v32, 16, v203
	v_mul_f32_e32 v32, 0xbfb8aa3b, v32
	v_exp_f32_e32 v32, v32
	v_pk_mul_f32 v[64:65], v[64:65], v[108:109]
	v_add_f32_e32 v32, 1.0, v32
	v_rcp_f32_e32 v102, v32
	v_and_b32_e32 v32, 0xffff0000, v203
	v_mul_f32_e32 v32, 0xbfb8aa3b, v32
	v_exp_f32_e32 v32, v32
	v_cvt_pk_bf16_f32 v64, v64, v65
	v_add_f32_e32 v32, 1.0, v32
	v_rcp_f32_e32 v103, v32
	v_lshlrev_b32_e32 v32, 16, v204
	v_mul_f32_e32 v32, 0xbfb8aa3b, v32
	v_exp_f32_e32 v32, v32
	v_pk_mul_f32 v[66:67], v[66:67], v[102:103]
	v_add_f32_e32 v32, 1.0, v32
	v_cvt_pk_bf16_f32 v65, v66, v67
	v_rcp_f32_e32 v66, v32
	v_and_b32_e32 v32, 0xffff0000, v204
	v_mul_f32_e32 v32, 0xbfb8aa3b, v32
	v_exp_f32_e32 v32, v32
	s_nop 0
	v_add_f32_e32 v32, 1.0, v32
	v_rcp_f32_e32 v67, v32
	v_lshlrev_b32_e32 v32, 16, v205
	v_mul_f32_e32 v32, 0xbfb8aa3b, v32
	v_exp_f32_e32 v32, v32
	v_pk_mul_f32 v[60:61], v[60:61], v[66:67]
	v_add_f32_e32 v32, 1.0, v32
	v_cvt_pk_bf16_f32 v66, v60, v61
	v_rcp_f32_e32 v60, v32
	v_and_b32_e32 v32, 0xffff0000, v205
	v_mul_f32_e32 v32, 0xbfb8aa3b, v32
	v_exp_f32_e32 v32, v32
	s_nop 0
	v_add_f32_e32 v32, 1.0, v32
	v_rcp_f32_e32 v61, v32
	s_waitcnt vmcnt(14)
; __device__ __forceinline__ unsigned cvt_pk_bf16(float lo, float hi) { const f32x2_t v = {lo, hi}; const bf16x2_t c = __builtin_convertvector(v, bf16x2_t); return __builtin_bit_cast(unsigned, c); }
; __device__ __forceinline__ float bf_lo(unsigned w) { return __uint_as_float(w << 16); }
; __device__ __forceinline__ float bf_hi(unsigned w) { return __uint_as_float(w & 0xffff0000u); }
; __device__ __forceinline__ float sigmoidf_fast(float x) { return __builtin_amdgcn_rcpf(1.0f + __expf(-x)); }
;     __device__ __forceinline__ void operator()(const f32x4 (&acc)[2][2][4][2], const Unit& u, int wr, int wc, int fr, int fq) const {
;     ...
;             for (int m = 0; m < 4; ++m) { const size_t r = (size_t)(row0 + ai * HALF + m * 16);
; #pragma unroll
;                 for (int bj = 0; bj < 2; ++bj) { const u32x4 gw = gq[m][bj]; const f32x4 a0 = acc[ai][bj][m][0], a1 = acc[ai][bj][m][1];
;                     u32x4 w; w.x = cvt_pk_bf16(sigmoidf_fast(bf_lo(gw.x)) * a0[0], sigmoidf_fast(bf_hi(gw.x)) * a0[1]); w.y = cvt_pk_bf16(sigmoidf_fast(bf_lo(gw.y)) * a0[2], sigmoidf_fast(bf_hi(gw.y)) * a0[3]);
;                     w.z = cvt_pk_bf16(sigmoidf_fast(bf_lo(gw.z)) * a1[0], sigmoidf_fast(bf_hi(gw.z)) * a1[1]); w.w = cvt_pk_bf16(sigmoidf_fast(bf_lo(gw.w)) * a1[2], sigmoidf_fast(bf_hi(gw.w)) * a1[3]);
;                     *(u32x4*)(T + r * ldt + col0 + bj * HALF) = w; } }
	v_lshlrev_b32_e32 v32, 16, v206
	v_mul_f32_e32 v32, 0xbfb8aa3b, v32
	v_exp_f32_e32 v32, v32
	v_pk_mul_f32 v[60:61], v[62:63], v[60:61]
	v_add_f32_e32 v32, 1.0, v32
	v_rcp_f32_e32 v62, v32
	v_and_b32_e32 v32, 0xffff0000, v206
	v_mul_f32_e32 v32, 0xbfb8aa3b, v32
	v_exp_f32_e32 v32, v32
	v_cvt_pk_bf16_f32 v67, v60, v61
	v_lshlrev_b64 v[60:61], 12, v[106:107]
	v_lshl_add_u64 v[60:61], s[22:23], 0, v[60:61]
	v_add_f32_e32 v32, 1.0, v32
	v_rcp_f32_e32 v63, v32
	v_lshlrev_b32_e32 v32, 16, v207
	v_mul_f32_e32 v32, 0xbfb8aa3b, v32
	v_exp_f32_e32 v32, v32
	v_pk_mul_f32 v[56:57], v[56:57], v[62:63]
	v_lshl_add_u64 v[60:61], v[60:61], 0, v[34:35]
	v_cvt_pk_bf16_f32 v56, v56, v57
	v_add_f32_e32 v32, 1.0, v32
	v_rcp_f32_e32 v62, v32
	v_and_b32_e32 v32, 0xffff0000, v207
	v_mul_f32_e32 v32, 0xbfb8aa3b, v32
	v_exp_f32_e32 v32, v32
	global_store_dwordx4 v[60:61], v[64:67], off
	v_add_f32_e32 v32, 1.0, v32
	v_rcp_f32_e32 v63, v32
	v_lshlrev_b32_e32 v32, 16, v208
	v_mul_f32_e32 v32, 0xbfb8aa3b, v32
	v_exp_f32_e32 v32, v32
	v_pk_mul_f32 v[58:59], v[58:59], v[62:63]
	v_add_f32_e32 v32, 1.0, v32
	v_cvt_pk_bf16_f32 v57, v58, v59
	v_rcp_f32_e32 v58, v32
	v_and_b32_e32 v32, 0xffff0000, v208
	v_mul_f32_e32 v32, 0xbfb8aa3b, v32
	v_exp_f32_e32 v32, v32
	s_nop 0
	v_add_f32_e32 v32, 1.0, v32
	v_rcp_f32_e32 v59, v32
	v_lshlrev_b32_e32 v32, 16, v209
	v_mul_f32_e32 v32, 0xbfb8aa3b, v32
	v_exp_f32_e32 v32, v32
	v_pk_mul_f32 v[52:53], v[52:53], v[58:59]
	v_add_f32_e32 v32, 1.0, v32
	v_cvt_pk_bf16_f32 v58, v52, v53
	v_rcp_f32_e32 v52, v32
	v_and_b32_e32 v32, 0xffff0000, v209
	v_mul_f32_e32 v32, 0xbfb8aa3b, v32
	v_exp_f32_e32 v32, v32
	s_nop 0
	v_add_f32_e32 v32, 1.0, v32
	v_rcp_f32_e32 v53, v32
	s_waitcnt vmcnt(14)
	v_lshlrev_b32_e32 v32, 16, v210
	v_mul_f32_e32 v32, 0xbfb8aa3b, v32
	v_exp_f32_e32 v32, v32
	v_pk_mul_f32 v[52:53], v[54:55], v[52:53]
	v_add_f32_e32 v32, 1.0, v32
	v_cvt_pk_bf16_f32 v59, v52, v53
	v_rcp_f32_e32 v52, v32
	v_and_b32_e32 v32, 0xffff0000, v210
	v_mul_f32_e32 v32, 0xbfb8aa3b, v32
	v_exp_f32_e32 v32, v32
	global_store_dwordx4 v[60:61], v[56:59], off offset:256
	v_add_f32_e32 v32, 1.0, v32
	v_rcp_f32_e32 v53, v32
	v_lshlrev_b32_e32 v32, 16, v211
	v_mul_f32_e32 v32, 0xbfb8aa3b, v32
	v_exp_f32_e32 v32, v32
	v_pk_mul_f32 v[48:49], v[48:49], v[52:53]
	v_add_f32_e32 v32, 1.0, v32
	v_rcp_f32_e32 v52, v32
	v_and_b32_e32 v32, 0xffff0000, v211
	v_mul_f32_e32 v32, 0xbfb8aa3b, v32
	v_exp_f32_e32 v32, v32
	v_cvt_pk_bf16_f32 v48, v48, v49
	v_add_f32_e32 v32, 1.0, v32
	v_rcp_f32_e32 v53, v32
	v_lshlrev_b32_e32 v32, 16, v212
	v_mul_f32_e32 v32, 0xbfb8aa3b, v32
	v_exp_f32_e32 v32, v32
	v_pk_mul_f32 v[50:51], v[50:51], v[52:53]
	v_add_f32_e32 v32, 1.0, v32
	v_cvt_pk_bf16_f32 v49, v50, v51
	v_rcp_f32_e32 v50, v32
	v_and_b32_e32 v32, 0xffff0000, v212
	v_mul_f32_e32 v32, 0xbfb8aa3b, v32
	v_exp_f32_e32 v32, v32
	s_nop 0
	v_add_f32_e32 v32, 1.0, v32
	v_rcp_f32_e32 v51, v32
	v_lshlrev_b32_e32 v32, 16, v213
	v_mul_f32_e32 v32, 0xbfb8aa3b, v32
	v_exp_f32_e32 v32, v32
	v_pk_mul_f32 v[44:45], v[44:45], v[50:51]
	v_add_f32_e32 v32, 1.0, v32
	v_cvt_pk_bf16_f32 v50, v44, v45
	v_rcp_f32_e32 v44, v32
	v_and_b32_e32 v32, 0xffff0000, v213
	v_mul_f32_e32 v32, 0xbfb8aa3b, v32
	v_exp_f32_e32 v32, v32
	s_nop 0
	v_add_f32_e32 v32, 1.0, v32
	v_rcp_f32_e32 v45, v32
	s_waitcnt vmcnt(14)
	v_lshlrev_b32_e32 v32, 16, v214
	v_mul_f32_e32 v32, 0xbfb8aa3b, v32
	v_exp_f32_e32 v32, v32
	v_pk_mul_f32 v[44:45], v[46:47], v[44:45]
	v_add_f32_e32 v32, 1.0, v32
	v_rcp_f32_e32 v46, v32
	v_and_b32_e32 v32, 0xffff0000, v214
	v_mul_f32_e32 v32, 0xbfb8aa3b, v32
	v_exp_f32_e32 v32, v32
	v_cvt_pk_bf16_f32 v51, v44, v45
	v_lshlrev_b64 v[44:45], 12, v[100:101]
	v_lshl_add_u64 v[44:45], s[22:23], 0, v[44:45]
	v_add_f32_e32 v32, 1.0, v32
	v_rcp_f32_e32 v47, v32
	v_lshlrev_b32_e32 v32, 16, v215
	v_mul_f32_e32 v32, 0xbfb8aa3b, v32
	v_exp_f32_e32 v32, v32
	v_pk_mul_f32 v[40:41], v[40:41], v[46:47]
	v_lshl_add_u64 v[44:45], v[44:45], 0, v[34:35]
	v_cvt_pk_bf16_f32 v40, v40, v41
	v_add_f32_e32 v32, 1.0, v32
	v_rcp_f32_e32 v46, v32
	v_and_b32_e32 v32, 0xffff0000, v215
	v_mul_f32_e32 v32, 0xbfb8aa3b, v32
	v_exp_f32_e32 v32, v32
	global_store_dwordx4 v[44:45], v[48:51], off
	v_add_f32_e32 v32, 1.0, v32
	v_rcp_f32_e32 v47, v32
	v_lshlrev_b32_e32 v32, 16, v216
	v_mul_f32_e32 v32, 0xbfb8aa3b, v32
	v_exp_f32_e32 v32, v32
	v_pk_mul_f32 v[42:43], v[42:43], v[46:47]
	v_add_f32_e32 v32, 1.0, v32
	v_cvt_pk_bf16_f32 v41, v42, v43
	v_rcp_f32_e32 v42, v32
	v_and_b32_e32 v32, 0xffff0000, v216
	v_mul_f32_e32 v32, 0xbfb8aa3b, v32
	v_exp_f32_e32 v32, v32
	s_nop 0
	v_add_f32_e32 v32, 1.0, v32
	v_rcp_f32_e32 v43, v32
	v_lshlrev_b32_e32 v32, 16, v217
	v_mul_f32_e32 v32, 0xbfb8aa3b, v32
	v_exp_f32_e32 v32, v32
	v_pk_mul_f32 v[36:37], v[36:37], v[42:43]
	v_add_f32_e32 v32, 1.0, v32
	v_cvt_pk_bf16_f32 v42, v36, v37
	v_rcp_f32_e32 v36, v32
	v_and_b32_e32 v32, 0xffff0000, v217
	v_mul_f32_e32 v32, 0xbfb8aa3b, v32
	v_exp_f32_e32 v32, v32
	s_nop 0
	v_add_f32_e32 v32, 1.0, v32
	v_rcp_f32_e32 v37, v32
	s_waitcnt vmcnt(14)
; __device__ __forceinline__ unsigned cvt_pk_bf16(float lo, float hi) { const f32x2_t v = {lo, hi}; const bf16x2_t c = __builtin_convertvector(v, bf16x2_t); return __builtin_bit_cast(unsigned, c); }
; __device__ __forceinline__ float bf_lo(unsigned w) { return __uint_as_float(w << 16); }
; __device__ __forceinline__ float bf_hi(unsigned w) { return __uint_as_float(w & 0xffff0000u); }
; __device__ __forceinline__ float sigmoidf_fast(float x) { return __builtin_amdgcn_rcpf(1.0f + __expf(-x)); }
;     __device__ __forceinline__ void operator()(const f32x4 (&acc)[2][2][4][2], const Unit& u, int wr, int wc, int fr, int fq) const {
;     ...
;             for (int m = 0; m < 4; ++m) { const size_t r = (size_t)(row0 + ai * HALF + m * 16);
; #pragma unroll
;                 for (int bj = 0; bj < 2; ++bj) { const u32x4 gw = gq[m][bj]; const f32x4 a0 = acc[ai][bj][m][0], a1 = acc[ai][bj][m][1];
;                     u32x4 w; w.x = cvt_pk_bf16(sigmoidf_fast(bf_lo(gw.x)) * a0[0], sigmoidf_fast(bf_hi(gw.x)) * a0[1]); w.y = cvt_pk_bf16(sigmoidf_fast(bf_lo(gw.y)) * a0[2], sigmoidf_fast(bf_hi(gw.y)) * a0[3]);
;                     w.z = cvt_pk_bf16(sigmoidf_fast(bf_lo(gw.z)) * a1[0], sigmoidf_fast(bf_hi(gw.z)) * a1[1]); w.w = cvt_pk_bf16(sigmoidf_fast(bf_lo(gw.w)) * a1[2], sigmoidf_fast(bf_hi(gw.w)) * a1[3]);
;                     *(u32x4*)(T + r * ldt + col0 + bj * HALF) = w; } }
	v_lshlrev_b32_e32 v32, 16, v218
	v_mul_f32_e32 v32, 0xbfb8aa3b, v32
	v_exp_f32_e32 v32, v32
	v_pk_mul_f32 v[36:37], v[38:39], v[36:37]
	v_add_f32_e32 v32, 1.0, v32
	v_cvt_pk_bf16_f32 v43, v36, v37
	v_rcp_f32_e32 v36, v32
	v_and_b32_e32 v32, 0xffff0000, v218
	v_mul_f32_e32 v32, 0xbfb8aa3b, v32
	v_exp_f32_e32 v32, v32
	global_store_dwordx4 v[44:45], v[40:43], off offset:256
	v_add_f32_e32 v32, 1.0, v32
	v_rcp_f32_e32 v37, v32
	s_nop 0
	v_pk_mul_f32 v[28:29], v[28:29], v[36:37]
	s_nop 0
	v_cvt_pk_bf16_f32 v28, v28, v29
	v_lshlrev_b32_e32 v29, 16, v219
	v_mul_f32_e32 v29, 0xbfb8aa3b, v29
	v_exp_f32_e32 v29, v29
	s_nop 0
	v_add_f32_e32 v29, 1.0, v29
	v_rcp_f32_e32 v36, v29
	v_and_b32_e32 v29, 0xffff0000, v219
	v_mul_f32_e32 v29, 0xbfb8aa3b, v29
	v_exp_f32_e32 v29, v29
	s_nop 0
	v_add_f32_e32 v29, 1.0, v29
	v_rcp_f32_e32 v37, v29
	s_nop 0
	v_pk_mul_f32 v[30:31], v[30:31], v[36:37]
	s_nop 0
	v_cvt_pk_bf16_f32 v29, v30, v31
	v_lshlrev_b32_e32 v30, 16, v220
	v_and_b32_e32 v31, 0xffff0000, v220
	v_mul_f32_e32 v30, 0xbfb8aa3b, v30
	v_mul_f32_e32 v31, 0xbfb8aa3b, v31
	v_exp_f32_e32 v30, v30
	v_exp_f32_e32 v31, v31
	v_add_f32_e32 v30, 1.0, v30
	v_add_f32_e32 v31, 1.0, v31
	v_rcp_f32_e32 v30, v30
	v_rcp_f32_e32 v31, v31
	s_nop 0
	v_pk_mul_f32 v[24:25], v[24:25], v[30:31]
	s_nop 0
	v_cvt_pk_bf16_f32 v30, v24, v25
	v_lshlrev_b32_e32 v24, 16, v221
	v_and_b32_e32 v25, 0xffff0000, v221
	v_mul_f32_e32 v24, 0xbfb8aa3b, v24
	v_mul_f32_e32 v25, 0xbfb8aa3b, v25
	v_exp_f32_e32 v24, v24
	v_exp_f32_e32 v25, v25
	v_add_f32_e32 v24, 1.0, v24
	v_add_f32_e32 v25, 1.0, v25
	v_rcp_f32_e32 v24, v24
	v_rcp_f32_e32 v25, v25
	s_nop 0
	v_pk_mul_f32 v[24:25], v[26:27], v[24:25]
	s_waitcnt vmcnt(14)
	v_lshlrev_b32_e32 v26, 16, v222
	v_and_b32_e32 v27, 0xffff0000, v222
	v_mul_f32_e32 v26, 0xbfb8aa3b, v26
	v_mul_f32_e32 v27, 0xbfb8aa3b, v27
	v_exp_f32_e32 v26, v26
	v_exp_f32_e32 v27, v27
	v_cvt_pk_bf16_f32 v31, v24, v25
	v_lshlrev_b64 v[24:25], 12, v[98:99]
	v_add_f32_e32 v26, 1.0, v26
	v_add_f32_e32 v27, 1.0, v27
	v_rcp_f32_e32 v26, v26
	v_rcp_f32_e32 v27, v27
	v_lshl_add_u64 v[24:25], s[22:23], 0, v[24:25]
	v_lshl_add_u64 v[24:25], v[24:25], 0, v[34:35]
	global_store_dwordx4 v[24:25], v[28:31], off
	v_pk_mul_f32 v[20:21], v[20:21], v[26:27]
	s_nop 0
	v_cvt_pk_bf16_f32 v20, v20, v21
	v_lshlrev_b32_e32 v21, 16, v223
	v_mul_f32_e32 v21, 0xbfb8aa3b, v21
	v_exp_f32_e32 v21, v21
	s_nop 0
	v_add_f32_e32 v21, 1.0, v21
	v_rcp_f32_e32 v26, v21
	v_and_b32_e32 v21, 0xffff0000, v223
	v_mul_f32_e32 v21, 0xbfb8aa3b, v21
	v_exp_f32_e32 v21, v21
	s_nop 0
	v_add_f32_e32 v21, 1.0, v21
	v_rcp_f32_e32 v27, v21
	s_nop 0
	v_pk_mul_f32 v[22:23], v[22:23], v[26:27]
	s_nop 0
	v_cvt_pk_bf16_f32 v21, v22, v23
	v_lshlrev_b32_e32 v22, 16, v224
	v_and_b32_e32 v23, 0xffff0000, v224
	v_mul_f32_e32 v22, 0xbfb8aa3b, v22
	v_mul_f32_e32 v23, 0xbfb8aa3b, v23
	v_exp_f32_e32 v22, v22
	v_exp_f32_e32 v23, v23
	v_add_f32_e32 v22, 1.0, v22
	v_add_f32_e32 v23, 1.0, v23
	v_rcp_f32_e32 v22, v22
	v_rcp_f32_e32 v23, v23
	s_nop 0
	v_pk_mul_f32 v[16:17], v[16:17], v[22:23]
	s_nop 0
	v_cvt_pk_bf16_f32 v22, v16, v17
	v_lshlrev_b32_e32 v16, 16, v225
	v_and_b32_e32 v17, 0xffff0000, v225
	v_mul_f32_e32 v16, 0xbfb8aa3b, v16
	v_mul_f32_e32 v17, 0xbfb8aa3b, v17
	v_exp_f32_e32 v16, v16
	v_exp_f32_e32 v17, v17
	v_add_f32_e32 v16, 1.0, v16
	v_add_f32_e32 v17, 1.0, v17
	v_rcp_f32_e32 v16, v16
	v_rcp_f32_e32 v17, v17
	s_nop 0
	v_pk_mul_f32 v[16:17], v[18:19], v[16:17]
	s_nop 0
	v_cvt_pk_bf16_f32 v23, v16, v17
	s_waitcnt vmcnt(6)
	v_lshlrev_b32_e32 v16, 16, v72
	v_and_b32_e32 v17, 0xffff0000, v72
	v_mul_f32_e32 v16, 0xbfb8aa3b, v16
	v_mul_f32_e32 v17, 0xbfb8aa3b, v17
	v_exp_f32_e32 v16, v16
	v_exp_f32_e32 v17, v17
	global_store_dwordx4 v[24:25], v[20:23], off offset:256
	v_add_f32_e32 v16, 1.0, v16
	v_add_f32_e32 v17, 1.0, v17
	v_rcp_f32_e32 v16, v16
	v_rcp_f32_e32 v17, v17
	s_nop 0
	v_pk_mul_f32 v[12:13], v[12:13], v[16:17]
	s_nop 0
	v_cvt_pk_bf16_f32 v12, v12, v13
	v_lshlrev_b32_e32 v13, 16, v73
	v_mul_f32_e32 v13, 0xbfb8aa3b, v13
	v_exp_f32_e32 v13, v13
	s_nop 0
	v_add_f32_e32 v13, 1.0, v13
	v_rcp_f32_e32 v16, v13
	v_and_b32_e32 v13, 0xffff0000, v73
	v_mul_f32_e32 v13, 0xbfb8aa3b, v13
	v_exp_f32_e32 v13, v13
	s_nop 0
	v_add_f32_e32 v13, 1.0, v13
	v_rcp_f32_e32 v17, v13
	s_nop 0
	v_pk_mul_f32 v[14:15], v[14:15], v[16:17]
	s_nop 0
	v_cvt_pk_bf16_f32 v13, v14, v15
	v_lshlrev_b32_e32 v14, 16, v74
	v_and_b32_e32 v15, 0xffff0000, v74
	v_mul_f32_e32 v14, 0xbfb8aa3b, v14
	v_mul_f32_e32 v15, 0xbfb8aa3b, v15
	v_exp_f32_e32 v14, v14
	v_exp_f32_e32 v15, v15
	v_add_f32_e32 v14, 1.0, v14
	v_add_f32_e32 v15, 1.0, v15
	v_rcp_f32_e32 v14, v14
	v_rcp_f32_e32 v15, v15
	s_nop 0
	v_pk_mul_f32 v[8:9], v[8:9], v[14:15]
	s_nop 0
	v_cvt_pk_bf16_f32 v14, v8, v9
	v_lshlrev_b32_e32 v8, 16, v75
	v_and_b32_e32 v9, 0xffff0000, v75
	v_mul_f32_e32 v8, 0xbfb8aa3b, v8
	v_mul_f32_e32 v9, 0xbfb8aa3b, v9
	v_exp_f32_e32 v8, v8
	v_exp_f32_e32 v9, v9
	v_add_f32_e32 v8, 1.0, v8
	v_add_f32_e32 v9, 1.0, v9
	v_rcp_f32_e32 v8, v8
	v_rcp_f32_e32 v9, v9
	s_nop 0
	v_pk_mul_f32 v[8:9], v[10:11], v[8:9]
	s_waitcnt vmcnt(6)
	v_lshlrev_b32_e32 v10, 16, v68
	v_and_b32_e32 v11, 0xffff0000, v68
	v_mul_f32_e32 v10, 0xbfb8aa3b, v10
	v_mul_f32_e32 v11, 0xbfb8aa3b, v11
	v_exp_f32_e32 v10, v10
	v_exp_f32_e32 v11, v11
	v_cvt_pk_bf16_f32 v15, v8, v9
	v_lshlrev_b64 v[8:9], 12, v[96:97]
	v_add_f32_e32 v10, 1.0, v10
	v_add_f32_e32 v11, 1.0, v11
	v_rcp_f32_e32 v10, v10
	v_rcp_f32_e32 v11, v11
	v_lshl_add_u64 v[8:9], s[22:23], 0, v[8:9]
	v_lshl_add_u64 v[8:9], v[8:9], 0, v[34:35]
	global_store_dwordx4 v[8:9], v[12:15], off
	v_pk_mul_f32 v[4:5], v[4:5], v[10:11]
	s_nop 0
	v_cvt_pk_bf16_f32 v4, v4, v5
	v_lshlrev_b32_e32 v5, 16, v69
	v_mul_f32_e32 v5, 0xbfb8aa3b, v5
	v_exp_f32_e32 v5, v5
	s_nop 0
	v_add_f32_e32 v5, 1.0, v5
	v_rcp_f32_e32 v10, v5
	v_and_b32_e32 v5, 0xffff0000, v69
	v_mul_f32_e32 v5, 0xbfb8aa3b, v5
	v_exp_f32_e32 v5, v5
	s_nop 0
	v_add_f32_e32 v5, 1.0, v5
	v_rcp_f32_e32 v11, v5
	s_nop 0
	v_pk_mul_f32 v[6:7], v[6:7], v[10:11]
	s_nop 0
	v_cvt_pk_bf16_f32 v5, v6, v7
	v_lshlrev_b32_e32 v6, 16, v70
	v_and_b32_e32 v7, 0xffff0000, v70
	v_mul_f32_e32 v6, 0xbfb8aa3b, v6
	v_mul_f32_e32 v7, 0xbfb8aa3b, v7
	v_exp_f32_e32 v6, v6
	v_exp_f32_e32 v7, v7
	v_add_f32_e32 v6, 1.0, v6
	v_add_f32_e32 v7, 1.0, v7
	v_rcp_f32_e32 v6, v6
	v_rcp_f32_e32 v7, v7
	s_nop 0
	v_pk_mul_f32 v[0:1], v[0:1], v[6:7]
	s_nop 0
	v_cvt_pk_bf16_f32 v6, v0, v1
	v_lshlrev_b32_e32 v0, 16, v71
	v_and_b32_e32 v1, 0xffff0000, v71
	v_mul_f32_e32 v0, 0xbfb8aa3b, v0
	v_mul_f32_e32 v1, 0xbfb8aa3b, v1
	v_exp_f32_e32 v0, v0
	v_exp_f32_e32 v1, v1
	v_add_f32_e32 v0, 1.0, v0
	v_add_f32_e32 v1, 1.0, v1
	v_rcp_f32_e32 v0, v0
	v_rcp_f32_e32 v1, v1
	s_nop 0
	v_pk_mul_f32 v[0:1], v[2:3], v[0:1]
	s_nop 0
	v_cvt_pk_bf16_f32 v7, v0, v1
	global_store_dwordx4 v[8:9], v[4:7], off offset:256
	s_cbranch_vccnz .LBB0_834
; #define PG8_LAS __attribute__((address_space(3)))
; #define PG8_BAR __builtin_amdgcn_s_barrier()
; template <class Epi, class Sched, bool ALIGN_EPI = false, bool SP2 = false, bool KHOOK = false>
; __device__ __forceinline__ void gemm_phase(PG8_LAS unsigned char* lds, const Gemm g, const Sched& S, const Epi& E, const int tid_in) {
;     ...
;     auto load_rr = [&](const Unit& uu) { if constexpr (KHOOK) { const int row = tid >> 1, hf = tid & 1; const f32x4 v = *(const f32x4*)(g.rr + ((size_t)(uu.pm * BM + row)) * 8 + 4 * hf);
;         PG8_LAS float* T = (PG8_LAS float*)(lds + 8 * 16384) + (4 * hf) * 256 + row; T[0] = v[0]; T[256] = v[1]; T[512] = v[2]; T[768] = v[3]; } };
;     ...
;         cur = nxt; cA = nA; cB = nB; ++ui; load_rr(cur);
;         if constexpr (ALIGN_EPI) { if (wr == 1) PG8_BAR; }
	v_lshl_add_u32 v0, s8, 8, v184
	v_ashrrev_i32_e32 v1, 31, v0
	v_lshlrev_b64 v[0:1], 5, v[0:1]
	v_lshl_add_u64 v[0:1], v[168:169], 0, v[0:1]
	global_load_dwordx4 v[0:3], v[0:1], off
	s_andn2_b64 vcc, exec, s[0:1]
	s_waitcnt vmcnt(0)
	ds_write2st64_b32 v185, v0, v1 offset1:4
	ds_write2st64_b32 v185, v2, v3 offset0:8 offset1:12
	s_cbranch_vccnz .LBB0_833
	s_barrier
	s_branch .LBB0_833
